# chains shortened to the gate-GEMM time: GLA staging load addresses hoisted out of the loop (SGPR base + fixed lane offsets), HGRN2 loader waves raised priority
# speedup vs baseline: 1.0172x; 1.0029x over previous
.LBB0_980:
	s_or_b64 exec, exec, s[6:7]
	s_ashr_i32 s0, s20, 6
	v_and_b32_e32 v16, 15, v86
	v_lshl_or_b32 v19, s0, 4, v16
	v_bfe_u32 v18, v86, 4, 2
	s_cmp_lt_i32 s0, 8
	v_mul_lo_u32 v19, v19, s63
	v_readlane_b32 s1, v254, 37
	s_mul_i32 s0, s0, 0xe000
	v_lshlrev_b32_e32 v53, 4, v18
	v_bfe_u32 v54, v86, 1, 3
	v_add_u32_e32 v55, s1, v19
	v_readlane_b32 s1, v254, 38
	v_lshlrev_b32_e32 v59, 3, v18
	v_mov_b32_e32 v18, s0
	v_add_u32_e32 v88, s1, v53
	v_readlane_b32 s1, v254, 39
	v_mul_u32_u24_e32 v91, 0x90, v16
	v_and_b32_e32 v16, 1, v86
	v_mad_u32_u24 v18, v54, s60, v18
	v_add_u32_e32 v52, 0, v19
	v_add_u32_e32 v56, s1, v53
	v_readlane_b32 s1, v254, 40
	v_lshlrev_b32_e32 v16, 7, v16
	v_ashrrev_i32_e32 v19, 31, v18
	v_add_u32_e32 v57, s1, v53
	v_readlane_b32 s1, v254, 41
	v_lshl_or_b32 v16, s17, 8, v16
	v_lshlrev_b64 v[18:19], 1, v[18:19]
	v_add_u32_e32 v58, s1, v53
	v_readlane_b32 s1, v254, 42
	v_or3_b32 v18, v16, v59, v18
	s_waitcnt lgkmcnt(0)
	s_barrier
	v_add_u32_e32 v89, s1, v53
	v_readlane_b32 s1, v254, 43
	v_lshl_add_u64 v[84:85], v[18:19], 0, s[4:5]
	v_mov_b32_e32 v18, v17
	v_mov_b32_e32 v19, v17
	v_add_u32_e32 v87, 0, v53
	v_add_u32_e32 v90, s1, v53
	v_mov_b32_e32 v16, v17
	v_add_u32_e32 v92, v52, v53
	v_add_u32_e32 v93, v55, v53
	v_add_u32_e32 v94, v56, v91
	v_add_u32_e32 v95, v57, v91
	v_add_u32_e32 v96, v58, v91
	v_mov_b64_e32 v[54:55], v[18:19]
	v_mov_b64_e32 v[58:59], v[18:19]
	v_mov_b64_e32 v[62:63], v[18:19]
	v_mov_b64_e32 v[66:67], v[18:19]
	s_cselect_b64 s[6:7], -1, 0
	s_mov_b32 s17, 0
	v_mov_b64_e32 v[52:53], v[16:17]
	v_mov_b64_e32 v[56:57], v[16:17]
	v_mov_b64_e32 v[60:61], v[16:17]
	v_mov_b64_e32 v[64:65], v[16:17]
	v_lshrrev_b32_e32 v102, 3, v86
	v_mul_lo_u32 v102, v102, s60
	v_and_b32_e32 v103, 7, v86
	v_lshlrev_b32_e32 v103, 3, v103
	v_add3_u32 v97, v102, s11, v103
	v_lshlrev_b32_e32 v97, 1, v97
	v_lshlrev_b32_e32 v104, 3, v86
	v_and_b32_e32 v105, 56, v104
	v_add_u32_e32 v98, s16, v102
	v_or_b32_e32 v98, v98, v105
	v_lshlrev_b32_e32 v98, 1, v98
	v_add_u32_e32 v99, s13, v102
	v_or_b32_e32 v99, v99, v105
	v_lshlrev_b32_e32 v99, 1, v99
	v_and_b32_e32 v104, 0x78, v104
	v_or_b32_e32 v104, s12, v104
	v_lshrrev_b32_e32 v103, 4, v86
	v_mul_lo_u32 v103, v103, s60
	v_add_u32_e32 v100, v103, v104
	v_lshlrev_b32_e32 v100, 1, v100
	v_add_u32_e32 v103, 0x200, v86
	v_lshrrev_b32_e32 v103, 4, v103
	v_mul_lo_u32 v103, v103, s60
	v_add_u32_e32 v101, v103, v104
	v_lshlrev_b32_e32 v101, 1, v101
	s_branch .LBB0_983

.Lgla_wd:
	ds_write_b128 v68, v[4:7]
	v_add_u32_e32 v68, s8, v71
	v_mad_u64_u32 v[70:71], s[8:9], v70, s63, v[68:69]
	ds_write_b128 v70, v[8:11] offset:17408
	ds_write_b128 v70, v[12:15] offset:26624
	v_mad_u64_u32 v[70:71], s[8:9], v74, s63, v[68:69]
	v_mad_u64_u32 v[68:69], s[8:9], v73, s63, v[68:69]
	ds_write_b128 v70, v[20:23] offset:45056
	ds_write_b128 v68, v[24:27] offset:45056
	s_and_saveexec_b64 s[8:9], vcc
	v_add_u32_e32 v16, 0, v16
	v_add_u32_e32 v16, 0x1fc00, v16
	ds_write_b128 v16, v[0:3]
	s_or_b64 exec, exec, s[8:9]
	s_cmp_gt_u32 s17, 60
	s_cbranch_scc1 .LBB0_991
	s_add_u32 s8, s82, s4
	s_addc_u32 s9, s83, s5
	s_add_u32 s8, s8, 0x2a0000
	s_addc_u32 s9, s9, 0
	global_load_dwordx4 v[4:7], v97, s[8:9]
	global_load_dwordx4 v[8:11], v98, s[8:9]
	global_load_dwordx4 v[12:15], v99, s[8:9]
	global_load_dwordx4 v[20:23], v100, s[8:9]
	global_load_dwordx4 v[24:27], v101, s[8:9]
	v_mov_b32_e32 v68, v86
	v_cmp_gt_i32_e32 vcc, 48, v68
	s_and_saveexec_b64 s[8:9], vcc
	s_cbranch_execz .LBB0_990
	v_lshlrev_b32_e32 v0, 2, v68
	s_add_u32 s20, s82, s10
	v_ashrrev_i32_e32 v1, 31, v0
	s_addc_u32 s21, s83, s2
	v_lshl_add_u64 v[0:1], v[0:1], 2, s[20:21]
	v_add_co_u32_e32 v0, vcc, 0x1f7c0000, v0
	s_nop 1
	v_addc_co_u32_e32 v1, vcc, 0, v1, vcc
	global_load_dwordx4 v[0:3], v[0:1], off offset:2304

.LBB0_998:
	s_add_u32 s0, s82, s4
	s_addc_u32 s1, s83, s5
	s_add_u32 s0, s0, 0x380000
	s_addc_u32 s1, s1, 0
	global_load_dwordx4 v[32:35], v97, s[0:1]
	global_load_dwordx4 v[36:39], v98, s[0:1]
	global_load_dwordx4 v[40:43], v99, s[0:1]
	global_load_dwordx4 v[44:47], v100, s[0:1]
	global_load_dwordx4 v[48:51], v101, s[0:1]
	v_mov_b32_e32 v18, v86
	v_cmp_gt_i32_e32 vcc, 48, v18
	s_and_saveexec_b64 s[0:1], vcc
	s_cbranch_execz .LBB0_981
	v_lshlrev_b32_e32 v18, 2, v18
	s_add_u32 s8, s82, s10
	v_ashrrev_i32_e32 v19, 31, v18
	s_addc_u32 s9, s83, s2
	v_lshl_add_u64 v[18:19], v[18:19], 2, s[8:9]
	v_add_co_u32_e32 v18, vcc, 0x1f7c0000, v18
	s_nop 1
	v_addc_co_u32_e32 v19, vcc, 0, v19, vcc
	global_load_dwordx4 v[28:31], v[18:19], off offset:3072
	s_branch .LBB0_981

.LBB0_1017:
	s_or_b64 exec, exec, s[4:5]
	s_waitcnt lgkmcnt(0)
	s_barrier
	s_mov_b32 s6, 0
	s_setprio 3
	s_branch .LBB0_1020

.LBB0_1037:
	s_setprio 0
	s_waitcnt lgkmcnt(0)
	s_barrier
